# work rebalancing in the l0 mixer phase: context attention units of blocks 128-255 (which carry two retention units) moved to blocks 0-127
# baseline (speedup 1.0000x reference)
.LBB0_1044:
	s_add_i32 s26, s26, 1
	s_mul_i32 s10, s26, s56
	s_cmp_gt_u32 s26, 2
	s_cbranch_scc1 .LBB0_1095

.LBB0_1049:
	s_cmp_eq_u32 s26, 0
	s_cselect_b32 s6, 15, 1
	s_cselect_b32 s8, s20, s19
	s_add_i32 s8, s18, s8
	s_and_b32 s6, s6, s17
	s_or_b32 s6, s8, s6
	s_cmp_eq_u32 s26, 2
	s_cselect_b32 s98, 16, 0
	s_add_i32 s6, s6, s98
	s_cmp_eq_u32 s26, 0
	s_cselect_b32 s98, 0, 0x200
	s_cmp_gt_u32 s30, 127
	s_cselect_b32 s98, s98, 0
	s_or_b32 s6, s6, s98
	s_cmpk_gt_i32 s6, 0x1ff
	s_cbranch_scc1 .LBB0_1044
